# v20 plus a counted wait at the end of the P4/P6 epilogues (vmcnt(2)) so the K-loop restarts with the baseline's small store backlog
# speedup vs baseline: 1.0057x; 1.0057x over previous
; #define PG8_BAR __builtin_amdgcn_s_barrier()
; template <class Epi, class Sched, bool ALIGN_EPI = false, bool SP2 = false>
; __device__ __forceinline__ void gemm_phase(PG8_LAS unsigned char* lds, const Gemm g, const Sched& S, const Epi& E, const int wave_s) {
;     ...
;         if constexpr (!Epi::AFTER_DRAIN) { if constexpr (Epi::HAS_PRE) E(acc, cur, wr, wc, fr, fq, pf); else E(acc, cur, wr, wc, fr, fq); S.done(cur); }
;         if (!has_next) break;
; #pragma unroll
;         for (int a = 0; a < 2; ++a)
; #pragma unroll
;             for (int b = 0; b < 2; ++b)
; #pragma unroll
;                 for (int m = 0; m < 4; ++m)
; #pragma unroll
;                     for (int n = 0; n < 2; ++n) acc[a][b][m][n] = (f32x4){0.f, 0.f, 0.f, 0.f};
;         cur = nxt; cA = nA; cB = nB; ++ui;
;         if constexpr (ALIGN_EPI) { if (wr == 1) PG8_BAR; }
.LBB0_715:
	s_or_b64 exec, exec, s[60:61]
	s_waitcnt vmcnt(2)
	s_andn2_b64 vcc, exec, s[6:7]
	s_mov_b64 s[6:7], -1
	s_cbranch_vccnz .LBB0_692
	s_andn2_b64 vcc, exec, s[20:21]
	s_cbranch_vccnz .LBB0_691
	s_barrier
	s_branch .LBB0_691

; #define PG8_BAR __builtin_amdgcn_s_barrier()
; template <class Epi, class Sched, bool ALIGN_EPI = false, bool SP2 = false>
; __device__ __forceinline__ void gemm_phase(PG8_LAS unsigned char* lds, const Gemm g, const Sched& S, const Epi& E, const int wave_s) {
;     ...
;         if constexpr (!Epi::AFTER_DRAIN) { if constexpr (Epi::HAS_PRE) E(acc, cur, wr, wc, fr, fq, pf); else E(acc, cur, wr, wc, fr, fq); S.done(cur); }
;         if (!has_next) break;
; #pragma unroll
;         for (int a = 0; a < 2; ++a)
; #pragma unroll
;             for (int b = 0; b < 2; ++b)
; #pragma unroll
;                 for (int m = 0; m < 4; ++m)
; #pragma unroll
;                     for (int n = 0; n < 2; ++n) acc[a][b][m][n] = (f32x4){0.f, 0.f, 0.f, 0.f};
;         cur = nxt; cA = nA; cB = nB; ++ui;
;         if constexpr (ALIGN_EPI) { if (wr == 1) PG8_BAR; }
.LBB0_875:
	s_or_b64 exec, exec, s[44:45]
	s_waitcnt vmcnt(2)
	s_andn2_b64 vcc, exec, s[4:5]
	s_mov_b64 s[4:5], -1
	s_cbranch_vccnz .LBB0_852
	s_andn2_b64 vcc, exec, s[6:7]
	s_cbranch_vccnz .LBB0_851
	s_barrier
	s_branch .LBB0_851
